# P6 tail: the four final-gain vector loads issued up front with the other loads (were load/wait/store serial after the reduction, each wait also covering the previous store); on top of v78
# speedup vs baseline: 1.0259x; 1.0259x over previous
; __device__ __forceinline__ void sample_finalize(const Args& a) {
;     ...
;     for (int r = gw; r < MS; r += NGW) {
;         f32x4 v[4]; float ss = 0.f;
; #pragma unroll
;         for (int j = 0; j < 4; ++j) { const int col = 4 * lane + 256 * j;
;             f32x4 p = *(const f32x4*)(part + (size_t)r * DM + col);
; #pragma unroll
;             for (int ks = 1; ks < 4; ++ks) p += *(const f32x4*)(part + ((size_t)ks * MS + r) * DM + col);
;             v[j] = *(const f32x4*)(a.in[1] + (size_t)r * DM + col) + *(const f32x4*)(gatef + (16 + (r >> 5)) * DM + col) * p;
;             ss += (v[j][0] * v[j][0] + v[j][1] * v[j][1]) + (v[j][2] * v[j][2] + v[j][3] * v[j][3]); }
.LBB0_1314:
	v_lshl_add_u64 v[90:91], s[2:3], 0, v[0:1]
	v_add_co_u32_e32 v50, vcc, 0x1e900000, v90
	v_lshl_add_u64 v[30:31], s[6:7], 0, v[0:1]
	s_nop 0
	v_addc_co_u32_e32 v51, vcc, 0, v91, vcc
	v_add_co_u32_e32 v92, vcc, 0x1ed00000, v90
	s_and_b32 s8, s10, 0xfffffc00
	global_load_dwordx4 v[14:17], v[30:31], off
	global_load_dwordx4 v[18:21], v[30:31], off offset:1024
	global_load_dwordx4 v[22:25], v[30:31], off offset:2048
	global_load_dwordx4 v[26:29], v[30:31], off offset:3072
	v_addc_co_u32_e32 v93, vcc, 0, v91, vcc
	global_load_dwordx4 v[30:33], v[50:51], off
	global_load_dwordx4 v[34:37], v[50:51], off offset:1024
	global_load_dwordx4 v[38:41], v[50:51], off offset:2048
	global_load_dwordx4 v[42:45], v[50:51], off offset:3072
	global_load_dwordx4 v[46:49], v[92:93], off
	s_addk_i32 s8, 0x4000
	v_add_co_u32_e32 v94, vcc, 0x1f100000, v90
	s_ashr_i32 s9, s8, 31
	s_nop 0
	v_addc_co_u32_e32 v95, vcc, 0, v91, vcc
	v_lshl_add_u64 v[110:111], s[8:9], 2, v[4:5]
	v_add_co_u32_e32 v112, vcc, 0x1f500000, v90
	global_load_dwordx4 v[50:53], v[92:93], off offset:1024
	global_load_dwordx4 v[54:57], v[92:93], off offset:2048
	global_load_dwordx4 v[58:61], v[110:111], off
	global_load_dwordx4 v[62:65], v[110:111], off offset:1024
	global_load_dwordx4 v[66:69], v[92:93], off offset:3072
	global_load_dwordx4 v[70:73], v[110:111], off offset:2048
	global_load_dwordx4 v[74:77], v[94:95], off
	global_load_dwordx4 v[78:81], v[94:95], off offset:1024
	global_load_dwordx4 v[82:85], v[94:95], off offset:2048
	global_load_dwordx4 v[86:89], v[94:95], off offset:3072
	v_addc_co_u32_e32 v113, vcc, 0, v91, vcc
	global_load_dwordx4 v[90:93], v[112:113], off
	global_load_dwordx4 v[94:97], v[112:113], off offset:1024
	global_load_dwordx4 v[98:101], v[112:113], off offset:2048
	global_load_dwordx4 v[102:105], v[112:113], off offset:3072
	global_load_dwordx4 v[106:109], v[110:111], off offset:3072
	s_add_i32 s8, s0, 0x8000
	global_load_dwordx4 v[110:113], v[2:3], off
	global_load_dwordx4 v[116:119], v[2:3], off offset:1024
	global_load_dwordx4 v[120:123], v[2:3], off offset:2048
	global_load_dwordx4 v[124:127], v[2:3], off offset:3072
	s_ashr_i32 s9, s8, 31
	s_lshl_b64 s[8:9], s[8:9], 12
	v_lshl_add_u64 v[114:115], v[6:7], 0, s[8:9]
	s_add_i32 s0, s0, s34
	s_add_i32 s10, s10, s11
	s_add_u32 s2, s2, s4
	s_addc_u32 s3, s3, s5
	s_add_u32 s6, s6, s4
	s_addc_u32 s7, s7, s5
	s_cmpk_lt_i32 s0, 0x400
	s_waitcnt vmcnt(19)
	v_pk_add_f32 v[32:33], v[32:33], v[48:49]
	v_pk_add_f32 v[30:31], v[30:31], v[46:47]
	s_waitcnt vmcnt(18)
	v_pk_add_f32 v[36:37], v[36:37], v[52:53]
	v_pk_add_f32 v[34:35], v[34:35], v[50:51]
	s_waitcnt vmcnt(17)
	v_pk_add_f32 v[40:41], v[40:41], v[56:57]
	v_pk_add_f32 v[38:39], v[38:39], v[54:55]
	s_waitcnt vmcnt(14)
	v_pk_add_f32 v[42:43], v[42:43], v[66:67]
	s_waitcnt vmcnt(12)
	v_pk_add_f32 v[32:33], v[32:33], v[76:77]
	v_pk_add_f32 v[30:31], v[30:31], v[74:75]
	s_waitcnt vmcnt(11)
	v_pk_add_f32 v[36:37], v[36:37], v[80:81]
	v_pk_add_f32 v[34:35], v[34:35], v[78:79]
	s_waitcnt vmcnt(8)
	v_pk_add_f32 v[32:33], v[32:33], v[92:93]
	v_pk_add_f32 v[30:31], v[30:31], v[90:91]
	s_waitcnt vmcnt(7)
	v_pk_add_f32 v[36:37], v[36:37], v[96:97]
	v_pk_add_f32 v[34:35], v[34:35], v[94:95]
	v_pk_add_f32 v[44:45], v[44:45], v[68:69]
	v_pk_add_f32 v[40:41], v[40:41], v[84:85]
	v_pk_add_f32 v[38:39], v[38:39], v[82:83]
	v_pk_add_f32 v[42:43], v[42:43], v[86:87]
	v_pk_fma_f32 v[16:17], v[32:33], v[60:61], v[16:17]
	v_pk_fma_f32 v[14:15], v[30:31], v[58:59], v[14:15]
	v_pk_fma_f32 v[20:21], v[36:37], v[64:65], v[20:21]
	v_pk_fma_f32 v[18:19], v[34:35], v[62:63], v[18:19]
	v_pk_add_f32 v[44:45], v[44:45], v[88:89]
	s_waitcnt vmcnt(6)
; __device__ __forceinline__ void sample_finalize(const Args& a) {
;     ...
;         const float rr = rsqrtf(wave_sum(ss) * (1.f / DM) + EPS);
; #pragma unroll
;         for (int j = 0; j < 4; ++j) { const int col = 4 * lane + 256 * j; *(f32x4*)(a.out + (size_t)(MP + r) * DM + col) = v[j] * rr * *(const f32x4*)(a.in[18] + col); }
	v_pk_add_f32 v[40:41], v[40:41], v[100:101]
	v_pk_add_f32 v[38:39], v[38:39], v[98:99]
	s_waitcnt vmcnt(5)
	v_pk_add_f32 v[42:43], v[42:43], v[102:103]
	v_pk_mul_f32 v[30:31], v[16:17], v[16:17]
	v_pk_mul_f32 v[32:33], v[14:15], v[14:15]
	v_pk_mul_f32 v[34:35], v[20:21], v[20:21]
	v_pk_mul_f32 v[36:37], v[18:19], v[18:19]
	v_pk_add_f32 v[44:45], v[44:45], v[104:105]
	v_pk_fma_f32 v[24:25], v[40:41], v[72:73], v[24:25]
	v_pk_fma_f32 v[22:23], v[38:39], v[70:71], v[22:23]
	s_waitcnt vmcnt(4)
	v_pk_fma_f32 v[26:27], v[42:43], v[106:107], v[26:27]
	v_pk_mov_b32 v[42:43], v[32:33], v[30:31] op_sel:[1,0]
	v_mov_b32_e32 v33, v31
	v_pk_mov_b32 v[30:31], v[36:37], v[34:35] op_sel:[1,0]
	v_mov_b32_e32 v37, v35
	v_pk_fma_f32 v[28:29], v[44:45], v[108:109], v[28:29]
	v_mul_f32_e32 v41, v27, v27
	v_mul_f32_e32 v38, v23, v23
	v_mul_f32_e32 v40, v25, v25
	v_pk_add_f32 v[32:33], v[42:43], v[32:33]
	v_pk_add_f32 v[30:31], v[30:31], v[36:37]
	v_mul_f32_e32 v13, v26, v26
	v_mul_f32_e32 v44, v28, v28
	v_mul_f32_e32 v45, v29, v29
	v_pk_fma_f32 v[34:35], v[22:23], v[22:23], v[38:39] op_sel_hi:[1,1,0]
	v_pk_fma_f32 v[38:39], v[24:25], v[24:25], v[40:41] op_sel_hi:[1,1,0]
	v_pk_add_f32 v[32:33], v[32:33], v[32:33] op_sel:[0,1] op_sel_hi:[1,0]
	v_pk_add_f32 v[30:31], v[30:31], v[30:31] op_sel:[0,1] op_sel_hi:[1,0]
	v_mov_b32_e32 v35, v44
	v_mov_b32_e32 v39, v45
	v_mov_b32_e32 v33, v13
	v_mov_b32_e32 v31, v41
	v_pk_add_f32 v[34:35], v[34:35], v[38:39]
	v_pk_add_f32 v[30:31], v[32:33], v[30:31]
	s_nop 0
	v_pk_add_f32 v[30:31], v[30:31], v[34:35]
	s_nop 0
	v_add_f32_e32 v13, v30, v31
	ds_bpermute_b32 v30, v8, v13
	s_waitcnt lgkmcnt(0)
	v_add_f32_e32 v13, v13, v30
	ds_bpermute_b32 v30, v9, v13
	s_waitcnt lgkmcnt(0)
	v_add_f32_e32 v13, v13, v30
	ds_bpermute_b32 v30, v10, v13
	s_waitcnt lgkmcnt(0)
	v_add_f32_e32 v13, v13, v30
	ds_bpermute_b32 v30, v11, v13
	s_waitcnt lgkmcnt(0)
	v_add_f32_e32 v13, v13, v30
	ds_bpermute_b32 v30, v177, v13
	s_waitcnt lgkmcnt(0)
	v_add_f32_e32 v13, v13, v30
	ds_bpermute_b32 v30, v178, v13
	s_waitcnt lgkmcnt(0)
	v_add_f32_e32 v13, v13, v30
	v_fmamk_f32 v13, v13, 0x3a800000, v12
	v_mul_f32_e32 v30, 0x4b800000, v13
	v_cmp_gt_f32_e32 vcc, s1, v13
	s_nop 1
	v_cndmask_b32_e32 v13, v13, v30, vcc
	v_rsq_f32_e32 v13, v13
	s_nop 0
	v_mul_f32_e32 v30, 0x45800000, v13
	v_cndmask_b32_e32 v30, v13, v30, vcc
	v_pk_mul_f32 v[14:15], v[14:15], v[30:31] op_sel_hi:[1,0]
	v_pk_mul_f32 v[16:17], v[16:17], v[30:31] op_sel_hi:[1,0]
	s_waitcnt vmcnt(0)
	v_pk_mul_f32 v[14:15], v[110:111], v[14:15]
	v_pk_mul_f32 v[16:17], v[112:113], v[16:17]
	global_store_dwordx4 v[114:115], v[14:17], off
	v_pk_mul_f32 v[20:21], v[20:21], v[30:31] op_sel_hi:[1,0]
	v_pk_mul_f32 v[18:19], v[18:19], v[30:31] op_sel_hi:[1,0]
	v_pk_mul_f32 v[16:17], v[118:119], v[20:21]
	v_pk_mul_f32 v[14:15], v[116:117], v[18:19]
	global_store_dwordx4 v[114:115], v[14:17], off offset:1024
	v_pk_mul_f32 v[18:19], v[24:25], v[30:31] op_sel_hi:[1,0]
	v_pk_mul_f32 v[20:21], v[22:23], v[30:31] op_sel_hi:[1,0]
	v_pk_mul_f32 v[16:17], v[122:123], v[18:19]
	v_pk_mul_f32 v[14:15], v[120:121], v[20:21]
	global_store_dwordx4 v[114:115], v[14:17], off offset:2048
	v_pk_mul_f32 v[18:19], v[28:29], v[30:31] op_sel_hi:[1,0]
	v_pk_mul_f32 v[20:21], v[26:27], v[30:31] op_sel_hi:[1,0]
	v_pk_mul_f32 v[16:17], v[126:127], v[18:19]
	v_pk_mul_f32 v[14:15], v[124:125], v[20:21]
	global_store_dwordx4 v[114:115], v[14:17], off offset:3072
	s_cbranch_scc1 .LBB0_1314
